# scan S3 interval: priority 2 for waves 0,1 (the f32 Nab writers with eight ds_write_b32 each), reset to 0 at the start of S4+S1
# speedup vs baseline: 1.0003x; 1.0003x over previous
; __device__ __forceinline__ uint2 pack4(f32x4 v) { uint2 u; u.x = cvt_pk_bf16(v[0], v[1]); u.y = cvt_pk_bf16(v[2], v[3]); return u; }
; #define MFMA16(a, b, c) __builtin_amdgcn_mfma_f32_16x16x32_bf16(a, b, c, 0, 0, 0)
; __device__ __forceinline__ void scan_phase(PREF p, char* smem, const int wid_u) {
;     ...
;     for (int c = 0; c < nch; ++c) {
;       {
;         const int mat = wave >> 1, mts = wave & 1;
;         const bf16_t* As = (mat & 1) ? Kt : Bt;
;         const bf16_t* Bs = (mat & 2) ? Rt : At;
;         f32x4 acc[2] = {};
; #pragma unroll
;         for (int ks = 0; ks < 2; ++ks) {
;           const bf16x8 a = ldfrag(As, 72, mts * 16, ks * 32, fr, fq);
; #pragma unroll
;           for (int nt = 0; nt < 2; ++nt) acc[nt] = MFMA16(a, ldfrag(Bs, 72, nt * 16, ks * 32, fr, fq), acc[nt]);
;         }
; #pragma unroll
;         for (int nt = 0; nt < 2; ++nt) {
;           const int tcol = nt * 16 + fr;
;           f32x4 v = acc[nt];
; #pragma unroll
;           for (int jj = 0; jj < 4; ++jj) {
;             const int srow = mts * 16 + fq * 4 + jj;
;             const bool keep = (mat & 2) ? (srow <= tcol) : (srow < tcol);
;             v[jj] = keep ? v[jj] : 0.f;
;           }
;           if (mat == 0) {
; #pragma unroll
;             for (int jj = 0; jj < 4; ++jj) Nab[(mts * 16 + fq * 4 + jj) * 32 + tcol] = v[jj];
;           } else {
;             bf16_t* dst = mat == 1 ? NakT : mat == 2 ? NbrT : NkrT;
;             *(uint2*)(dst + tcol * 40 + mts * 16 + fq * 4) = pack4(v);
;           }
;         }
;       }
.LBB0_540:
	s_cmp_gt_u32 s90, 1
	s_cbranch_scc1 .Lprio_i1_skip
	s_setprio 2

; __device__ __forceinline__ uint2 pack4(f32x4 v) { uint2 u; u.x = cvt_pk_bf16(v[0], v[1]); u.y = cvt_pk_bf16(v[2], v[3]); return u; }
; #define MFMA16(a, b, c) __builtin_amdgcn_mfma_f32_16x16x32_bf16(a, b, c, 0, 0, 0)
; __device__ __forceinline__ void scan_phase(PREF p, char* smem, const int wid_u) {
;     ...
;       lds_barrier();
;       if (wave == 4) {
;         const int irow = lane >> 1, hb = lane & 1, blk = lane >> 5, il = irow & 15;
;         float x[8];
; #pragma unroll
;         for (int i = 0; i < 8; ++i) x[i] = (hb * 8 + i == il) ? 1.f : 0.f;
;         const float* nb = Nab + (blk * 16) * 32 + blk * 16 + hb * 8;
;         solve16<0>(x, nb);
; #pragma unroll
;         for (int i = 0; i < 8; ++i) TT[(blk * 16 + hb * 8 + i) * 40 + blk * 16 + il] = (bf16_t)(cvt_pk_bf16(x[i], 0.f) & 0xffff);
;         if (blk == 0) *(uint4*)(T11b + il * 40 + hb * 8) = pack8(x);
;         __builtin_amdgcn_wave_barrier();
;         const f32x4 zero = {0.f, 0.f, 0.f, 0.f};
;         bf16x8 zf;
; #pragma unroll
;         for (int i = 0; i < 8; ++i) zf[i] = 0;
;         bf16x8 n12 = zf, t22 = zf, t11 = zf;
;         if (fq < 2) {
;           float o[8];
;           const f32x4 n0 = *(const f32x4*)(Nab + fr * 32 + 16 + fq * 8), n1 = *(const f32x4*)(Nab + fr * 32 + 16 + fq * 8 + 4);
;           o[0] = n0[0]; o[1] = n0[1]; o[2] = n0[2]; o[3] = n0[3]; o[4] = n1[0]; o[5] = n1[1]; o[6] = n1[2]; o[7] = n1[3];
;           uint4 u = pack8(o);
;           n12 = *reinterpret_cast<bf16x8*>(&u);
;           t22 = *reinterpret_cast<const bf16x8*>(TT + (16 + fr) * 40 + 16 + fq * 8);
;           t11 = *reinterpret_cast<const bf16x8*>(T11b + fr * 40 + fq * 8);
;         }
;         const f32x4 m1 = MFMA16(n12, t22, zero);
;         *(uint2*)(M1T + fr * 40 + fq * 4) = pack4(m1);
;         __builtin_amdgcn_wave_barrier();
;         bf16x8 m1f = zf;
;         if (fq < 2) m1f = *reinterpret_cast<const bf16x8*>(M1T + fr * 40 + fq * 8);
;         const f32x4 t12 = MFMA16(t11, m1f, zero);
;         *(uint2*)(TT + (16 + fr) * 40 + fq * 4) = pack4(t12);
;       } else if (wave == 5) {
;         unsigned z0;
;         asm volatile("v_mov_b32 %0, 0" : "=v"(z0));
;         *(uint2*)(TT + (lane >> 2) * 40 + 16 + (lane & 3) * 4) = make_uint2(z0, z0);
;       } else if (wave == 2 || wave == 3 || wave >= 6) {
.LBB0_548:
	s_waitcnt lgkmcnt(0)
	s_barrier
	s_cmp_lt_u32 s90, 4
	s_cbranch_scc1 .Lprio_i2_lora
	s_cmp_eq_u32 s90, 5
	s_cbranch_scc1 .Lprio_i2_skip
	s_setprio 3
	s_branch .Lprio_i2_skip
.Lprio_i2_lora:
	s_setprio 0
.Lprio_i2_skip:
	s_mov_b64 s[82:83], -1
	s_mov_b64 s[40:41], 0
	s_cmp_lt_i32 s90, 5
	s_mov_b64 s[80:81], 0
	s_cbranch_scc0 .LBB0_552
	s_and_b64 vcc, exec, s[82:83]
	s_cbranch_vccnz .LBB0_555
